# byte-placement trial: outproj phase code shifted by 16 bytes, code after the phase kept in place
# baseline (speedup 1.0000x reference)
; template <int MB, bool PF2 = true>
; DI void gemm_main(const u16* __restrict__ A, int lda, const u16* __restrict__ B, int ldb, int K, f32x16 (&acc)[MB][2], GemmLds* s, int tid) {
;   const int lane = tid & 63, w = tid >> 6, r = lane & 31, h = lane >> 5, wm = w >> 1, wn = w & 1;
;   const int srow = tid >> 3, skc = (tid & 7) * 8;
;   const unsigned oa0 = (unsigned)(srow * lda + skc) * 2u, oa1 = oa0 + 64u * lda, oa2 = oa0 + 128u * lda, oa3 = oa0 + 192u * lda;
;   const unsigned ob0 = (unsigned)(srow * ldb + skc) * 2u, ob1 = ob0 + 64u * ldb, ob2 = ob0 + 128u * ldb, ob3 = ob0 + 192u * ldb;
; DI void phase_outproj(const Params& p, int l, char* smem, int tid) {
;   const int lane = tid & 63, w = tid >> 6, r = lane & 31, h = lane >> 5, wm = w >> 1, wn = w & 1;
;   GemmLds* s = (GemmLds*)smem;
;   const u16* ACC = p.Pk;
;   const bool dyn = (l == 0);
;   unsigned* qc = p.bar + 4096 + 384;
;   for (int it = (dyn ? fetch_item(qc, smem) : (int)blockIdx.x); it < 272 * 8; it = (dyn ? fetch_item(qc, smem) : it + (int)gridDim.x)) {
.LBB0_1221:
	s_or_b64 exec, exec, s[4:5]
	v_mov_b32_e32 v0, v206
	s_and_b64 vcc, exec, s[0:1]
	v_mov_b32_e32 v146, s48
	s_waitcnt lgkmcnt(0)
	s_barrier
	v_readlane_b32 s18, v254, 19
	v_and_b32_e32 v112, 63, v206
	v_lshrrev_b32_e32 v113, 6, v206
	v_lshrrev_b32_e32 v114, 3, v112
	v_lshl_add_u32 v114, v113, 5, v114
	v_lshlrev_b32_e32 v114, 11, v114
	v_and_b32_e32 v115, 7, v112
	v_lshrrev_b32_e32 v112, 4, v112
	v_xor_b32_e32 v115, v115, v112
	v_lshl_or_b32 v98, v115, 4, v114
	v_xor_b32_e32 v99, 64, v98
	v_add_u32_e32 v99, 16384, v99
	v_add_u32_e32 v100, 32768, v98
	v_add_u32_e32 v101, 32768, v99
	v_lshrrev_b32_e32 v156, 6, v206
	v_and_b32_e32 v112, 31, v206
	v_bfe_u32 v113, v206, 5, 1
	v_bfe_u32 v114, v112, 1, 3
	v_xor_b32_e32 v114, v114, v113
	v_lshlrev_b32_e32 v114, 4, v114
	v_lshl_or_b32 v114, v112, 7, v114
	v_lshrrev_b32_e32 v115, 7, v206
	v_lshl_add_u32 v102, v115, 13, v114
	v_bfe_u32 v115, v206, 6, 1
	v_lshl_add_u32 v106, v115, 13, v114
	v_add_u32_e32 v106, 0x4000, v106
	v_xor_b32_e32 v103, 32, v102
	v_xor_b32_e32 v107, 32, v106
	v_xor_b32_e32 v104, 64, v102
	v_xor_b32_e32 v108, 64, v106
	v_xor_b32_e32 v105, 96, v102
	v_xor_b32_e32 v109, 96, v106
	v_and_b32_e32 v112, 31, v206
	v_lshrrev_b32_e32 v113, 7, v206
	v_lshl_add_u32 v112, v113, 6, v112
	v_lshlrev_b32_e32 v112, 11, v112
	v_bfe_u32 v113, v206, 6, 1
	v_bfe_u32 v114, v206, 5, 1
	v_lshlrev_b32_e32 v115, 7, v113
	v_lshl_or_b32 v115, v114, 3, v115
	v_or_b32_e32 v110, v112, v115
	v_lshlrev_b32_e32 v111, 8, v113
	v_lshl_or_b32 v111, v114, 4, v111
	v_lshrrev_b32_e32 v112, 6, v206
	v_mul_u32_u24_e32 v112, 0x2400, v112
	v_and_b32_e32 v113, 31, v206
	v_mul_u32_u24_e32 v113, 0x90, v113
	v_bfe_u32 v114, v206, 5, 1
	v_lshl_add_u32 v113, v114, 3, v113
	v_add_u32_e32 v164, v112, v113
	v_bfe_u32 v113, v206, 3, 3
	v_mul_u32_u24_e32 v113, 0x90, v113
	v_and_b32_e32 v114, 7, v206
	v_lshl_add_u32 v113, v114, 4, v113
	v_add_u32_e32 v165, v112, v113
	v_bfe_u32 v112, v206, 3, 3
	v_lshrrev_b32_e32 v113, 7, v206
	v_lshl_add_u32 v112, v113, 6, v112
	v_mul_u32_u24_e32 v112, 0x800, v112
	v_bfe_u32 v113, v206, 6, 1
	v_lshlrev_b32_e32 v113, 7, v113
	v_and_b32_e32 v114, 7, v206
	v_lshl_or_b32 v113, v114, 4, v113
	v_add_u32_e32 v166, v112, v113
	v_readfirstlane_b32 s10, v156
	s_lshl_b32 s10, s10, 12
	s_lshl_b32 s6, s18, 21
	s_add_u32 s14, s96, 0x1cc00000
	s_addc_u32 s15, s97, 0
	s_add_u32 s14, s14, s6
	s_addc_u32 s15, s15, 0
	s_mov_b32 s12, s48
	s_nop 0
	s_nop 0
	s_nop 0
	s_nop 0
